# phase-6 fused epilogues: two staging register sets, the next batch of residual loads issued before waiting for the current one
# baseline (speedup 1.0000x reference)
; DI void rmsnorm_rows(const float* x, const float* g, bf16_t* outb, float* outf) {
;     ...
;       for (int i = 0; i < 4; ++i) ss[rr] += v[rr][i].x * v[rr][i].x + v[rr][i].y * v[rr][i].y + v[rr][i].z * v[rr][i].z + v[rr][i].w * v[rr][i].w;
;   DI void operator()(const f32x4 (&acc)[2][2][4][2], const Unit& u, int wr, int wc, int fr, int fq) const {
;     const int row0 = u.pm * BM + wr * 64 + fr, col0 = u.pn * BM + wc * 32 + 4 * fq;
; #pragma unroll
;     for (int ai = 0; ai < 2; ++ai)
; #pragma unroll
;       for (int mp = 0; mp < 2; ++mp) {
;         f32x4 xv[2][2][2];
; #pragma unroll
;         for (int mm = 0; mm < 2; ++mm)
; #pragma unroll
;           for (int bj = 0; bj < 2; ++bj)
; #pragma unroll
;             for (int n = 0; n < 2; ++n)
;               xv[mm][bj][n] = *(const f32x4*)(X + (size_t)(row0 + ai * HALF + (mp * 2 + mm) * 16) * 1024 + col0 + bj * HALF + n * 16);
; #pragma unroll
;         for (int mm = 0; mm < 2; ++mm)
; #pragma unroll
;           for (int bj = 0; bj < 2; ++bj)
; #pragma unroll
;             for (int n = 0; n < 2; ++n)
;               *(f32x4*)(O + (size_t)(row0 + ai * HALF + (mp * 2 + mm) * 16) * 1024 + col0 + bj * HALF + n * 16) = xv[mm][bj][n] + acc[ai][bj][mp * 2 + mm][n];
;       }
;   }
.Lfz_p1:
	s_mov_b32 s92, 1
	s_mov_b32 s90, s40
	s_mov_b32 s91, s41
	v_lshrrev_b32_e32 v191, 6, v201
	v_lshrrev_b32_e32 v192, 2, v191
	v_and_b32_e32 v193, 3, v191
	v_and_b32_e32 v194, 15, v201
	v_bfe_u32 v195, v201, 4, 2
	v_lshlrev_b32_e32 v190, 18, v192
	v_lshl_or_b32 v190, v194, 12, v190
	v_lshl_or_b32 v190, v193, 7, v190
	v_lshl_or_b32 v190, v195, 4, v190
	s_lshl_b32 s100, s40, 20
	s_lshl_b32 s101, s41, 10
	s_add_u32 s100, s100, s101
	s_add_u32 s100, s2, s100
	s_addc_u32 s101, s3, 0
	s_add_u32 s96, s100, 0x0
	s_addc_u32 s97, s101, 0
	global_load_dwordx4 v[150:153], v190, s[96:97]
	global_load_dwordx4 v[154:157], v190, s[96:97] offset:64
	global_load_dwordx4 v[158:161], v190, s[96:97] offset:512
	global_load_dwordx4 v[162:165], v190, s[96:97] offset:576
	s_add_u32 s96, s100, 0x10000
	s_addc_u32 s97, s101, 0
	global_load_dwordx4 v[166:169], v190, s[96:97]
	global_load_dwordx4 v[170:173], v190, s[96:97] offset:64
	global_load_dwordx4 v[174:177], v190, s[96:97] offset:512
	global_load_dwordx4 v[178:181], v190, s[96:97] offset:576
	s_add_u32 s96, s100, 0x20000
	s_addc_u32 s97, s101, 0
	global_load_dwordx4 v[210:213], v190, s[96:97]
	global_load_dwordx4 v[214:217], v190, s[96:97] offset:64
	global_load_dwordx4 v[218:221], v190, s[96:97] offset:512
	global_load_dwordx4 v[230:233], v190, s[96:97] offset:576
	s_add_u32 s96, s100, 0x30000
	s_addc_u32 s97, s101, 0
	global_load_dwordx4 v[234:237], v190, s[96:97]
	global_load_dwordx4 v[238:241], v190, s[96:97] offset:64
	global_load_dwordx4 v[242:245], v190, s[96:97] offset:512
	global_load_dwordx4 v[246:249], v190, s[96:97] offset:576
	s_waitcnt vmcnt(8)
	v_pk_add_f32 v[126:127], v[126:127], v[150:151]
	v_pk_add_f32 v[128:129], v[128:129], v[152:153]
	v_pk_add_f32 v[122:123], v[122:123], v[154:155]
	v_pk_add_f32 v[124:125], v[124:125], v[156:157]
	v_pk_add_f32 v[110:111], v[110:111], v[158:159]
	v_pk_add_f32 v[112:113], v[112:113], v[160:161]
	v_pk_add_f32 v[106:107], v[106:107], v[162:163]
	v_pk_add_f32 v[108:109], v[108:109], v[164:165]
	v_pk_add_f32 v[118:119], v[118:119], v[166:167]
	v_pk_add_f32 v[120:121], v[120:121], v[168:169]
	v_pk_add_f32 v[114:115], v[114:115], v[170:171]
	v_pk_add_f32 v[116:117], v[116:117], v[172:173]
	v_pk_add_f32 v[102:103], v[102:103], v[174:175]
	v_pk_add_f32 v[104:105], v[104:105], v[176:177]
	v_pk_add_f32 v[98:99], v[98:99], v[178:179]
	v_pk_add_f32 v[100:101], v[100:101], v[180:181]
	s_nop 0
	s_add_u32 s96, s100, 0x80000
	s_addc_u32 s97, s101, 0
	global_load_dwordx4 v[150:153], v190, s[96:97]
	global_load_dwordx4 v[154:157], v190, s[96:97] offset:64
	global_load_dwordx4 v[158:161], v190, s[96:97] offset:512
	global_load_dwordx4 v[162:165], v190, s[96:97] offset:576
	s_add_u32 s96, s100, 0x90000
	s_addc_u32 s97, s101, 0
	global_load_dwordx4 v[166:169], v190, s[96:97]
	global_load_dwordx4 v[170:173], v190, s[96:97] offset:64
	global_load_dwordx4 v[174:177], v190, s[96:97] offset:512
	global_load_dwordx4 v[178:181], v190, s[96:97] offset:576
	v_pk_mul_f32 v[196:197], v[126:127], v[126:127]
	v_pk_fma_f32 v[196:197], v[128:129], v[128:129], v[196:197]
	v_pk_fma_f32 v[196:197], v[122:123], v[122:123], v[196:197]
	v_pk_fma_f32 v[196:197], v[124:125], v[124:125], v[196:197]
	v_pk_fma_f32 v[196:197], v[110:111], v[110:111], v[196:197]
	v_pk_fma_f32 v[196:197], v[112:113], v[112:113], v[196:197]
	v_pk_fma_f32 v[196:197], v[106:107], v[106:107], v[196:197]
	v_pk_fma_f32 v[196:197], v[108:109], v[108:109], v[196:197]
	s_nop 0
	v_add_f32_e32 v182, v196, v197
	v_pk_mul_f32 v[196:197], v[118:119], v[118:119]
	v_pk_fma_f32 v[196:197], v[120:121], v[120:121], v[196:197]
	v_pk_fma_f32 v[196:197], v[114:115], v[114:115], v[196:197]
	v_pk_fma_f32 v[196:197], v[116:117], v[116:117], v[196:197]
	v_pk_fma_f32 v[196:197], v[102:103], v[102:103], v[196:197]
	v_pk_fma_f32 v[196:197], v[104:105], v[104:105], v[196:197]
	v_pk_fma_f32 v[196:197], v[98:99], v[98:99], v[196:197]
	v_pk_fma_f32 v[196:197], v[100:101], v[100:101], v[196:197]
	s_nop 0
	v_add_f32_e32 v183, v196, v197
	s_waitcnt vmcnt(8)
	v_pk_add_f32 v[94:95], v[94:95], v[210:211]
	v_pk_add_f32 v[96:97], v[96:97], v[212:213]
	v_pk_add_f32 v[90:91], v[90:91], v[214:215]
	v_pk_add_f32 v[92:93], v[92:93], v[216:217]
	v_pk_add_f32 v[78:79], v[78:79], v[218:219]
	v_pk_add_f32 v[80:81], v[80:81], v[220:221]
	v_pk_add_f32 v[74:75], v[74:75], v[230:231]
	v_pk_add_f32 v[76:77], v[76:77], v[232:233]
	v_pk_add_f32 v[86:87], v[86:87], v[234:235]
	v_pk_add_f32 v[88:89], v[88:89], v[236:237]
	v_pk_add_f32 v[82:83], v[82:83], v[238:239]
	v_pk_add_f32 v[84:85], v[84:85], v[240:241]
	v_pk_add_f32 v[70:71], v[70:71], v[242:243]
	v_pk_add_f32 v[72:73], v[72:73], v[244:245]
	v_pk_add_f32 v[66:67], v[66:67], v[246:247]
	v_pk_add_f32 v[68:69], v[68:69], v[248:249]
	s_nop 0
	s_add_u32 s96, s100, 0xa0000
	s_addc_u32 s97, s101, 0
	global_load_dwordx4 v[210:213], v190, s[96:97]
	global_load_dwordx4 v[214:217], v190, s[96:97] offset:64
	global_load_dwordx4 v[218:221], v190, s[96:97] offset:512
	global_load_dwordx4 v[230:233], v190, s[96:97] offset:576
	s_add_u32 s96, s100, 0xb0000
	s_addc_u32 s97, s101, 0
	global_load_dwordx4 v[234:237], v190, s[96:97]
	global_load_dwordx4 v[238:241], v190, s[96:97] offset:64
	global_load_dwordx4 v[242:245], v190, s[96:97] offset:512
	global_load_dwordx4 v[246:249], v190, s[96:97] offset:576
	v_pk_mul_f32 v[196:197], v[94:95], v[94:95]
	v_pk_fma_f32 v[196:197], v[96:97], v[96:97], v[196:197]
	v_pk_fma_f32 v[196:197], v[90:91], v[90:91], v[196:197]
	v_pk_fma_f32 v[196:197], v[92:93], v[92:93], v[196:197]
	v_pk_fma_f32 v[196:197], v[78:79], v[78:79], v[196:197]
	v_pk_fma_f32 v[196:197], v[80:81], v[80:81], v[196:197]
	v_pk_fma_f32 v[196:197], v[74:75], v[74:75], v[196:197]
	v_pk_fma_f32 v[196:197], v[76:77], v[76:77], v[196:197]
	s_nop 0
	v_add_f32_e32 v184, v196, v197
	v_pk_mul_f32 v[196:197], v[86:87], v[86:87]
	v_pk_fma_f32 v[196:197], v[88:89], v[88:89], v[196:197]
	v_pk_fma_f32 v[196:197], v[82:83], v[82:83], v[196:197]
	v_pk_fma_f32 v[196:197], v[84:85], v[84:85], v[196:197]
	v_pk_fma_f32 v[196:197], v[70:71], v[70:71], v[196:197]
	v_pk_fma_f32 v[196:197], v[72:73], v[72:73], v[196:197]
	v_pk_fma_f32 v[196:197], v[66:67], v[66:67], v[196:197]
	v_pk_fma_f32 v[196:197], v[68:69], v[68:69], v[196:197]
	s_nop 0
	v_add_f32_e32 v185, v196, v197
	s_waitcnt vmcnt(8)
; DI void rmsnorm_rows(const float* x, const float* g, bf16_t* outb, float* outf) {
;     ...
;       for (int i = 0; i < 4; ++i) ss[rr] += v[rr][i].x * v[rr][i].x + v[rr][i].y * v[rr][i].y + v[rr][i].z * v[rr][i].z + v[rr][i].w * v[rr][i].w;
;   DI void operator()(const f32x4 (&acc)[2][2][4][2], const Unit& u, int wr, int wc, int fr, int fq) const {
;     const int row0 = u.pm * BM + wr * 64 + fr, col0 = u.pn * BM + wc * 32 + 4 * fq;
; #pragma unroll
;     for (int ai = 0; ai < 2; ++ai)
; #pragma unroll
;       for (int mp = 0; mp < 2; ++mp) {
;         f32x4 xv[2][2][2];
; #pragma unroll
;         for (int mm = 0; mm < 2; ++mm)
; #pragma unroll
;           for (int bj = 0; bj < 2; ++bj)
; #pragma unroll
;             for (int n = 0; n < 2; ++n)
;               xv[mm][bj][n] = *(const f32x4*)(X + (size_t)(row0 + ai * HALF + (mp * 2 + mm) * 16) * 1024 + col0 + bj * HALF + n * 16);
; #pragma unroll
;         for (int mm = 0; mm < 2; ++mm)
; #pragma unroll
;           for (int bj = 0; bj < 2; ++bj)
; #pragma unroll
;             for (int n = 0; n < 2; ++n)
;               *(f32x4*)(O + (size_t)(row0 + ai * HALF + (mp * 2 + mm) * 16) * 1024 + col0 + bj * HALF + n * 16) = xv[mm][bj][n] + acc[ai][bj][mp * 2 + mm][n];
;       }
;   }
	v_pk_add_f32 v[62:63], v[62:63], v[150:151]
	v_pk_add_f32 v[64:65], v[64:65], v[152:153]
	v_pk_add_f32 v[58:59], v[58:59], v[154:155]
	v_pk_add_f32 v[60:61], v[60:61], v[156:157]
	v_pk_add_f32 v[46:47], v[46:47], v[158:159]
	v_pk_add_f32 v[48:49], v[48:49], v[160:161]
	v_pk_add_f32 v[42:43], v[42:43], v[162:163]
	v_pk_add_f32 v[44:45], v[44:45], v[164:165]
	v_pk_add_f32 v[54:55], v[54:55], v[166:167]
	v_pk_add_f32 v[56:57], v[56:57], v[168:169]
	v_pk_add_f32 v[50:51], v[50:51], v[170:171]
	v_pk_add_f32 v[52:53], v[52:53], v[172:173]
	v_pk_add_f32 v[38:39], v[38:39], v[174:175]
	v_pk_add_f32 v[40:41], v[40:41], v[176:177]
	v_pk_add_f32 v[34:35], v[34:35], v[178:179]
	v_pk_add_f32 v[36:37], v[36:37], v[180:181]
	v_pk_mul_f32 v[196:197], v[62:63], v[62:63]
	v_pk_fma_f32 v[196:197], v[64:65], v[64:65], v[196:197]
	v_pk_fma_f32 v[196:197], v[58:59], v[58:59], v[196:197]
	v_pk_fma_f32 v[196:197], v[60:61], v[60:61], v[196:197]
	v_pk_fma_f32 v[196:197], v[46:47], v[46:47], v[196:197]
	v_pk_fma_f32 v[196:197], v[48:49], v[48:49], v[196:197]
	v_pk_fma_f32 v[196:197], v[42:43], v[42:43], v[196:197]
	v_pk_fma_f32 v[196:197], v[44:45], v[44:45], v[196:197]
	s_nop 0
	v_add_f32_e32 v186, v196, v197
	v_pk_mul_f32 v[196:197], v[54:55], v[54:55]
	v_pk_fma_f32 v[196:197], v[56:57], v[56:57], v[196:197]
	v_pk_fma_f32 v[196:197], v[50:51], v[50:51], v[196:197]
	v_pk_fma_f32 v[196:197], v[52:53], v[52:53], v[196:197]
	v_pk_fma_f32 v[196:197], v[38:39], v[38:39], v[196:197]
	v_pk_fma_f32 v[196:197], v[40:41], v[40:41], v[196:197]
	v_pk_fma_f32 v[196:197], v[34:35], v[34:35], v[196:197]
	v_pk_fma_f32 v[196:197], v[36:37], v[36:37], v[196:197]
	s_nop 0
	v_add_f32_e32 v187, v196, v197
	s_waitcnt vmcnt(0)
	v_pk_add_f32 v[30:31], v[30:31], v[210:211]
	v_pk_add_f32 v[32:33], v[32:33], v[212:213]
	v_pk_add_f32 v[26:27], v[26:27], v[214:215]
	v_pk_add_f32 v[28:29], v[28:29], v[216:217]
	v_pk_add_f32 v[14:15], v[14:15], v[218:219]
	v_pk_add_f32 v[16:17], v[16:17], v[220:221]
	v_pk_add_f32 v[10:11], v[10:11], v[230:231]
	v_pk_add_f32 v[12:13], v[12:13], v[232:233]
	v_pk_add_f32 v[22:23], v[22:23], v[234:235]
	v_pk_add_f32 v[24:25], v[24:25], v[236:237]
	v_pk_add_f32 v[18:19], v[18:19], v[238:239]
	v_pk_add_f32 v[20:21], v[20:21], v[240:241]
	v_pk_add_f32 v[6:7], v[6:7], v[242:243]
	v_pk_add_f32 v[8:9], v[8:9], v[244:245]
	v_pk_add_f32 v[2:3], v[2:3], v[246:247]
	v_pk_add_f32 v[4:5], v[4:5], v[248:249]
	v_pk_mul_f32 v[196:197], v[30:31], v[30:31]
	v_pk_fma_f32 v[196:197], v[32:33], v[32:33], v[196:197]
	v_pk_fma_f32 v[196:197], v[26:27], v[26:27], v[196:197]
	v_pk_fma_f32 v[196:197], v[28:29], v[28:29], v[196:197]
	v_pk_fma_f32 v[196:197], v[14:15], v[14:15], v[196:197]
	v_pk_fma_f32 v[196:197], v[16:17], v[16:17], v[196:197]
	v_pk_fma_f32 v[196:197], v[10:11], v[10:11], v[196:197]
	v_pk_fma_f32 v[196:197], v[12:13], v[12:13], v[196:197]
	s_nop 0
	v_add_f32_e32 v188, v196, v197
	v_pk_mul_f32 v[196:197], v[22:23], v[22:23]
	v_pk_fma_f32 v[196:197], v[24:25], v[24:25], v[196:197]
	v_pk_fma_f32 v[196:197], v[18:19], v[18:19], v[196:197]
	v_pk_fma_f32 v[196:197], v[20:21], v[20:21], v[196:197]
	v_pk_fma_f32 v[196:197], v[6:7], v[6:7], v[196:197]
	v_pk_fma_f32 v[196:197], v[8:9], v[8:9], v[196:197]
	v_pk_fma_f32 v[196:197], v[2:3], v[2:3], v[196:197]
	v_pk_fma_f32 v[196:197], v[4:5], v[4:5], v[196:197]
	s_nop 0
	v_add_f32_e32 v189, v196, v197
	v_mov_b32_e32 v130, v18
	v_mov_b32_e32 v131, v19
	v_mov_b32_e32 v132, v20
	v_mov_b32_e32 v133, v21
	v_mov_b32_e32 v134, v14
	v_mov_b32_e32 v135, v15
	v_mov_b32_e32 v136, v16
	v_mov_b32_e32 v137, v17
	v_mov_b32_e32 v138, v10
	v_mov_b32_e32 v139, v11
	v_mov_b32_e32 v140, v12
	v_mov_b32_e32 v141, v13
	v_mov_b32_e32 v142, v6
	v_mov_b32_e32 v143, v7
	v_mov_b32_e32 v144, v8
	v_mov_b32_e32 v145, v9
	v_mov_b32_e32 v146, v2
	v_mov_b32_e32 v147, v3
	v_mov_b32_e32 v148, v4
	v_mov_b32_e32 v149, v5
	s_and_b64 vcc, exec, s[36:37]
	s_mov_b64 s[42:43], s[38:39]
	s_mov_b64 s[44:45], s[34:35]
	s_branch .Lfz_p1_ret
.Lfz_p1b:
	s_mov_b32 s92, 2
	s_mov_b32 s90, s40
	s_mov_b32 s91, s41
	v_lshrrev_b32_e32 v191, 6, v201
	v_lshrrev_b32_e32 v192, 2, v191
	v_and_b32_e32 v193, 3, v191
	v_and_b32_e32 v194, 15, v201
	v_bfe_u32 v195, v201, 4, 2
	v_lshlrev_b32_e32 v190, 18, v192
	v_lshl_or_b32 v190, v194, 12, v190
	v_lshl_or_b32 v190, v193, 7, v190
	v_lshl_or_b32 v190, v195, 4, v190
	s_lshl_b32 s88, s40, 20
	s_lshl_b32 s93, s41, 10
	s_add_u32 s88, s88, s93
	s_add_u32 s100, s2, s88
	s_addc_u32 s101, s3, 0
	s_add_u32 s98, s4, s88
	s_addc_u32 s99, s5, 0
	s_add_u32 s96, s100, 0x0
	s_addc_u32 s97, s101, 0
	global_load_dwordx4 v[150:153], v190, s[96:97]
	global_load_dwordx4 v[154:157], v190, s[96:97] offset:64
	global_load_dwordx4 v[158:161], v190, s[96:97] offset:512
	global_load_dwordx4 v[162:165], v190, s[96:97] offset:576
	s_add_u32 s96, s100, 0x10000
	s_addc_u32 s97, s101, 0
	global_load_dwordx4 v[166:169], v190, s[96:97]
	global_load_dwordx4 v[170:173], v190, s[96:97] offset:64
	global_load_dwordx4 v[174:177], v190, s[96:97] offset:512
	global_load_dwordx4 v[178:181], v190, s[96:97] offset:576
	s_add_u32 s96, s100, 0x20000
	s_addc_u32 s97, s101, 0
	global_load_dwordx4 v[210:213], v190, s[96:97]
	global_load_dwordx4 v[214:217], v190, s[96:97] offset:64
	global_load_dwordx4 v[218:221], v190, s[96:97] offset:512
	global_load_dwordx4 v[230:233], v190, s[96:97] offset:576
	s_add_u32 s96, s100, 0x30000
	s_addc_u32 s97, s101, 0
	global_load_dwordx4 v[234:237], v190, s[96:97]
	global_load_dwordx4 v[238:241], v190, s[96:97] offset:64
	global_load_dwordx4 v[242:245], v190, s[96:97] offset:512
	global_load_dwordx4 v[246:249], v190, s[96:97] offset:576
	s_waitcnt vmcnt(8)
; DI void rmsnorm_rows(const float* x, const float* g, bf16_t* outb, float* outf) {
;     ...
;       for (int i = 0; i < 4; ++i) ss[rr] += v[rr][i].x * v[rr][i].x + v[rr][i].y * v[rr][i].y + v[rr][i].z * v[rr][i].z + v[rr][i].w * v[rr][i].w;
;   DI void operator()(const f32x4 (&acc)[2][2][4][2], const Unit& u, int wr, int wc, int fr, int fq) const {
;     const int row0 = u.pm * BM + wr * 64 + fr, col0 = u.pn * BM + wc * 32 + 4 * fq;
; #pragma unroll
;     for (int ai = 0; ai < 2; ++ai)
; #pragma unroll
;       for (int mp = 0; mp < 2; ++mp) {
;         f32x4 xv[2][2][2];
; #pragma unroll
;         for (int mm = 0; mm < 2; ++mm)
; #pragma unroll
;           for (int bj = 0; bj < 2; ++bj)
; #pragma unroll
;             for (int n = 0; n < 2; ++n)
;               xv[mm][bj][n] = *(const f32x4*)(X + (size_t)(row0 + ai * HALF + (mp * 2 + mm) * 16) * 1024 + col0 + bj * HALF + n * 16);
; #pragma unroll
;         for (int mm = 0; mm < 2; ++mm)
; #pragma unroll
;           for (int bj = 0; bj < 2; ++bj)
; #pragma unroll
;             for (int n = 0; n < 2; ++n)
;               *(f32x4*)(O + (size_t)(row0 + ai * HALF + (mp * 2 + mm) * 16) * 1024 + col0 + bj * HALF + n * 16) = xv[mm][bj][n] + acc[ai][bj][mp * 2 + mm][n];
;       }
;   }
	s_add_u32 s94, s98, 0x0
	s_addc_u32 s95, s99, 0
	v_pk_add_f32 v[126:127], v[126:127], v[150:151]
	v_pk_add_f32 v[128:129], v[128:129], v[152:153]
	global_store_dwordx4 v190, v[126:129], s[94:95]
	v_pk_add_f32 v[122:123], v[122:123], v[154:155]
	v_pk_add_f32 v[124:125], v[124:125], v[156:157]
	global_store_dwordx4 v190, v[122:125], s[94:95] offset:64
	v_pk_add_f32 v[110:111], v[110:111], v[158:159]
	v_pk_add_f32 v[112:113], v[112:113], v[160:161]
	global_store_dwordx4 v190, v[110:113], s[94:95] offset:512
	v_pk_add_f32 v[106:107], v[106:107], v[162:163]
	v_pk_add_f32 v[108:109], v[108:109], v[164:165]
	global_store_dwordx4 v190, v[106:109], s[94:95] offset:576
	s_add_u32 s94, s98, 0x10000
	s_addc_u32 s95, s99, 0
	v_pk_add_f32 v[118:119], v[118:119], v[166:167]
	v_pk_add_f32 v[120:121], v[120:121], v[168:169]
	global_store_dwordx4 v190, v[118:121], s[94:95]
	v_pk_add_f32 v[114:115], v[114:115], v[170:171]
	v_pk_add_f32 v[116:117], v[116:117], v[172:173]
	global_store_dwordx4 v190, v[114:117], s[94:95] offset:64
	v_pk_add_f32 v[102:103], v[102:103], v[174:175]
	v_pk_add_f32 v[104:105], v[104:105], v[176:177]
	global_store_dwordx4 v190, v[102:105], s[94:95] offset:512
	v_pk_add_f32 v[98:99], v[98:99], v[178:179]
	v_pk_add_f32 v[100:101], v[100:101], v[180:181]
	global_store_dwordx4 v190, v[98:101], s[94:95] offset:576
	s_nop 0
	s_add_u32 s96, s100, 0x80000
	s_addc_u32 s97, s101, 0
	global_load_dwordx4 v[150:153], v190, s[96:97]
	global_load_dwordx4 v[154:157], v190, s[96:97] offset:64
	global_load_dwordx4 v[158:161], v190, s[96:97] offset:512
	global_load_dwordx4 v[162:165], v190, s[96:97] offset:576
	s_add_u32 s96, s100, 0x90000
	s_addc_u32 s97, s101, 0
	global_load_dwordx4 v[166:169], v190, s[96:97]
	global_load_dwordx4 v[170:173], v190, s[96:97] offset:64
	global_load_dwordx4 v[174:177], v190, s[96:97] offset:512
	global_load_dwordx4 v[178:181], v190, s[96:97] offset:576
	v_pk_mul_f32 v[196:197], v[126:127], v[126:127]
	v_pk_fma_f32 v[196:197], v[128:129], v[128:129], v[196:197]
	v_pk_fma_f32 v[196:197], v[122:123], v[122:123], v[196:197]
	v_pk_fma_f32 v[196:197], v[124:125], v[124:125], v[196:197]
	v_pk_fma_f32 v[196:197], v[110:111], v[110:111], v[196:197]
	v_pk_fma_f32 v[196:197], v[112:113], v[112:113], v[196:197]
	v_pk_fma_f32 v[196:197], v[106:107], v[106:107], v[196:197]
	v_pk_fma_f32 v[196:197], v[108:109], v[108:109], v[196:197]
	s_nop 0
	v_add_f32_e32 v182, v196, v197
	v_pk_mul_f32 v[196:197], v[118:119], v[118:119]
	v_pk_fma_f32 v[196:197], v[120:121], v[120:121], v[196:197]
	v_pk_fma_f32 v[196:197], v[114:115], v[114:115], v[196:197]
	v_pk_fma_f32 v[196:197], v[116:117], v[116:117], v[196:197]
	v_pk_fma_f32 v[196:197], v[102:103], v[102:103], v[196:197]
	v_pk_fma_f32 v[196:197], v[104:105], v[104:105], v[196:197]
	v_pk_fma_f32 v[196:197], v[98:99], v[98:99], v[196:197]
	v_pk_fma_f32 v[196:197], v[100:101], v[100:101], v[196:197]
	s_nop 0
	v_add_f32_e32 v183, v196, v197
	s_waitcnt vmcnt(16)
	s_add_u32 s94, s98, 0x20000
	s_addc_u32 s95, s99, 0
	v_pk_add_f32 v[94:95], v[94:95], v[210:211]
	v_pk_add_f32 v[96:97], v[96:97], v[212:213]
	global_store_dwordx4 v190, v[94:97], s[94:95]
	v_pk_add_f32 v[90:91], v[90:91], v[214:215]
	v_pk_add_f32 v[92:93], v[92:93], v[216:217]
	global_store_dwordx4 v190, v[90:93], s[94:95] offset:64
	v_pk_add_f32 v[78:79], v[78:79], v[218:219]
	v_pk_add_f32 v[80:81], v[80:81], v[220:221]
	global_store_dwordx4 v190, v[78:81], s[94:95] offset:512
	v_pk_add_f32 v[74:75], v[74:75], v[230:231]
	v_pk_add_f32 v[76:77], v[76:77], v[232:233]
	global_store_dwordx4 v190, v[74:77], s[94:95] offset:576
	s_add_u32 s94, s98, 0x30000
	s_addc_u32 s95, s99, 0
	v_pk_add_f32 v[86:87], v[86:87], v[234:235]
	v_pk_add_f32 v[88:89], v[88:89], v[236:237]
	global_store_dwordx4 v190, v[86:89], s[94:95]
	v_pk_add_f32 v[82:83], v[82:83], v[238:239]
	v_pk_add_f32 v[84:85], v[84:85], v[240:241]
	global_store_dwordx4 v190, v[82:85], s[94:95] offset:64
	v_pk_add_f32 v[70:71], v[70:71], v[242:243]
	v_pk_add_f32 v[72:73], v[72:73], v[244:245]
	global_store_dwordx4 v190, v[70:73], s[94:95] offset:512
	v_pk_add_f32 v[66:67], v[66:67], v[246:247]
	v_pk_add_f32 v[68:69], v[68:69], v[248:249]
	global_store_dwordx4 v190, v[66:69], s[94:95] offset:576
	s_nop 0
	s_add_u32 s96, s100, 0xa0000
	s_addc_u32 s97, s101, 0
	global_load_dwordx4 v[210:213], v190, s[96:97]
	global_load_dwordx4 v[214:217], v190, s[96:97] offset:64
	global_load_dwordx4 v[218:221], v190, s[96:97] offset:512
	global_load_dwordx4 v[230:233], v190, s[96:97] offset:576
	s_add_u32 s96, s100, 0xb0000
	s_addc_u32 s97, s101, 0
	global_load_dwordx4 v[234:237], v190, s[96:97]
	global_load_dwordx4 v[238:241], v190, s[96:97] offset:64
	global_load_dwordx4 v[242:245], v190, s[96:97] offset:512
	global_load_dwordx4 v[246:249], v190, s[96:97] offset:576
	v_pk_mul_f32 v[196:197], v[94:95], v[94:95]
	v_pk_fma_f32 v[196:197], v[96:97], v[96:97], v[196:197]
	v_pk_fma_f32 v[196:197], v[90:91], v[90:91], v[196:197]
	v_pk_fma_f32 v[196:197], v[92:93], v[92:93], v[196:197]
	v_pk_fma_f32 v[196:197], v[78:79], v[78:79], v[196:197]
	v_pk_fma_f32 v[196:197], v[80:81], v[80:81], v[196:197]
	v_pk_fma_f32 v[196:197], v[74:75], v[74:75], v[196:197]
	v_pk_fma_f32 v[196:197], v[76:77], v[76:77], v[196:197]
	s_nop 0
	v_add_f32_e32 v184, v196, v197
	v_pk_mul_f32 v[196:197], v[86:87], v[86:87]
	v_pk_fma_f32 v[196:197], v[88:89], v[88:89], v[196:197]
	v_pk_fma_f32 v[196:197], v[82:83], v[82:83], v[196:197]
	v_pk_fma_f32 v[196:197], v[84:85], v[84:85], v[196:197]
	v_pk_fma_f32 v[196:197], v[70:71], v[70:71], v[196:197]
	v_pk_fma_f32 v[196:197], v[72:73], v[72:73], v[196:197]
	v_pk_fma_f32 v[196:197], v[66:67], v[66:67], v[196:197]
	v_pk_fma_f32 v[196:197], v[68:69], v[68:69], v[196:197]
	s_nop 0
	v_add_f32_e32 v185, v196, v197
	s_waitcnt vmcnt(16)
; DI void rmsnorm_rows(const float* x, const float* g, bf16_t* outb, float* outf) {
;     ...
;       for (int i = 0; i < 4; ++i) ss[rr] += v[rr][i].x * v[rr][i].x + v[rr][i].y * v[rr][i].y + v[rr][i].z * v[rr][i].z + v[rr][i].w * v[rr][i].w;
;   DI void operator()(const f32x4 (&acc)[2][2][4][2], const Unit& u, int wr, int wc, int fr, int fq) const {
;     const int row0 = u.pm * BM + wr * 64 + fr, col0 = u.pn * BM + wc * 32 + 4 * fq;
; #pragma unroll
;     for (int ai = 0; ai < 2; ++ai)
; #pragma unroll
;       for (int mp = 0; mp < 2; ++mp) {
;         f32x4 xv[2][2][2];
; #pragma unroll
;         for (int mm = 0; mm < 2; ++mm)
; #pragma unroll
;           for (int bj = 0; bj < 2; ++bj)
; #pragma unroll
;             for (int n = 0; n < 2; ++n)
;               xv[mm][bj][n] = *(const f32x4*)(X + (size_t)(row0 + ai * HALF + (mp * 2 + mm) * 16) * 1024 + col0 + bj * HALF + n * 16);
; #pragma unroll
;         for (int mm = 0; mm < 2; ++mm)
; #pragma unroll
;           for (int bj = 0; bj < 2; ++bj)
; #pragma unroll
;             for (int n = 0; n < 2; ++n)
;               *(f32x4*)(O + (size_t)(row0 + ai * HALF + (mp * 2 + mm) * 16) * 1024 + col0 + bj * HALF + n * 16) = xv[mm][bj][n] + acc[ai][bj][mp * 2 + mm][n];
;       }
;   }
	s_add_u32 s94, s98, 0x80000
	s_addc_u32 s95, s99, 0
	v_pk_add_f32 v[62:63], v[62:63], v[150:151]
	v_pk_add_f32 v[64:65], v[64:65], v[152:153]
	global_store_dwordx4 v190, v[62:65], s[94:95]
	v_pk_add_f32 v[58:59], v[58:59], v[154:155]
	v_pk_add_f32 v[60:61], v[60:61], v[156:157]
	global_store_dwordx4 v190, v[58:61], s[94:95] offset:64
	v_pk_add_f32 v[46:47], v[46:47], v[158:159]
	v_pk_add_f32 v[48:49], v[48:49], v[160:161]
	global_store_dwordx4 v190, v[46:49], s[94:95] offset:512
	v_pk_add_f32 v[42:43], v[42:43], v[162:163]
	v_pk_add_f32 v[44:45], v[44:45], v[164:165]
	global_store_dwordx4 v190, v[42:45], s[94:95] offset:576
	s_add_u32 s94, s98, 0x90000
	s_addc_u32 s95, s99, 0
	v_pk_add_f32 v[54:55], v[54:55], v[166:167]
	v_pk_add_f32 v[56:57], v[56:57], v[168:169]
	global_store_dwordx4 v190, v[54:57], s[94:95]
	v_pk_add_f32 v[50:51], v[50:51], v[170:171]
	v_pk_add_f32 v[52:53], v[52:53], v[172:173]
	global_store_dwordx4 v190, v[50:53], s[94:95] offset:64
	v_pk_add_f32 v[38:39], v[38:39], v[174:175]
	v_pk_add_f32 v[40:41], v[40:41], v[176:177]
	global_store_dwordx4 v190, v[38:41], s[94:95] offset:512
	v_pk_add_f32 v[34:35], v[34:35], v[178:179]
	v_pk_add_f32 v[36:37], v[36:37], v[180:181]
	global_store_dwordx4 v190, v[34:37], s[94:95] offset:576
	v_pk_mul_f32 v[196:197], v[62:63], v[62:63]
	v_pk_fma_f32 v[196:197], v[64:65], v[64:65], v[196:197]
	v_pk_fma_f32 v[196:197], v[58:59], v[58:59], v[196:197]
	v_pk_fma_f32 v[196:197], v[60:61], v[60:61], v[196:197]
	v_pk_fma_f32 v[196:197], v[46:47], v[46:47], v[196:197]
	v_pk_fma_f32 v[196:197], v[48:49], v[48:49], v[196:197]
	v_pk_fma_f32 v[196:197], v[42:43], v[42:43], v[196:197]
	v_pk_fma_f32 v[196:197], v[44:45], v[44:45], v[196:197]
	s_nop 0
	v_add_f32_e32 v186, v196, v197
	v_pk_mul_f32 v[196:197], v[54:55], v[54:55]
	v_pk_fma_f32 v[196:197], v[56:57], v[56:57], v[196:197]
	v_pk_fma_f32 v[196:197], v[50:51], v[50:51], v[196:197]
	v_pk_fma_f32 v[196:197], v[52:53], v[52:53], v[196:197]
	v_pk_fma_f32 v[196:197], v[38:39], v[38:39], v[196:197]
	v_pk_fma_f32 v[196:197], v[40:41], v[40:41], v[196:197]
	v_pk_fma_f32 v[196:197], v[34:35], v[34:35], v[196:197]
	v_pk_fma_f32 v[196:197], v[36:37], v[36:37], v[196:197]
	s_nop 0
	v_add_f32_e32 v187, v196, v197
	s_waitcnt vmcnt(8)
	s_add_u32 s94, s98, 0xa0000
	s_addc_u32 s95, s99, 0
	v_pk_add_f32 v[30:31], v[30:31], v[210:211]
	v_pk_add_f32 v[32:33], v[32:33], v[212:213]
	global_store_dwordx4 v190, v[30:33], s[94:95]
	v_pk_add_f32 v[26:27], v[26:27], v[214:215]
	v_pk_add_f32 v[28:29], v[28:29], v[216:217]
	global_store_dwordx4 v190, v[26:29], s[94:95] offset:64
	v_pk_add_f32 v[14:15], v[14:15], v[218:219]
	v_pk_add_f32 v[16:17], v[16:17], v[220:221]
	global_store_dwordx4 v190, v[14:17], s[94:95] offset:512
	v_pk_add_f32 v[10:11], v[10:11], v[230:231]
	v_pk_add_f32 v[12:13], v[12:13], v[232:233]
	global_store_dwordx4 v190, v[10:13], s[94:95] offset:576
	s_add_u32 s94, s98, 0xb0000
	s_addc_u32 s95, s99, 0
	v_pk_add_f32 v[22:23], v[22:23], v[234:235]
	v_pk_add_f32 v[24:25], v[24:25], v[236:237]
	global_store_dwordx4 v190, v[22:25], s[94:95]
	v_pk_add_f32 v[18:19], v[18:19], v[238:239]
	v_pk_add_f32 v[20:21], v[20:21], v[240:241]
	global_store_dwordx4 v190, v[18:21], s[94:95] offset:64
	v_pk_add_f32 v[6:7], v[6:7], v[242:243]
	v_pk_add_f32 v[8:9], v[8:9], v[244:245]
	global_store_dwordx4 v190, v[6:9], s[94:95] offset:512
	v_pk_add_f32 v[2:3], v[2:3], v[246:247]
	v_pk_add_f32 v[4:5], v[4:5], v[248:249]
	global_store_dwordx4 v190, v[2:5], s[94:95] offset:576
	v_pk_mul_f32 v[196:197], v[30:31], v[30:31]
	v_pk_fma_f32 v[196:197], v[32:33], v[32:33], v[196:197]
	v_pk_fma_f32 v[196:197], v[26:27], v[26:27], v[196:197]
	v_pk_fma_f32 v[196:197], v[28:29], v[28:29], v[196:197]
	v_pk_fma_f32 v[196:197], v[14:15], v[14:15], v[196:197]
	v_pk_fma_f32 v[196:197], v[16:17], v[16:17], v[196:197]
	v_pk_fma_f32 v[196:197], v[10:11], v[10:11], v[196:197]
	v_pk_fma_f32 v[196:197], v[12:13], v[12:13], v[196:197]
	s_nop 0
	v_add_f32_e32 v188, v196, v197
	v_pk_mul_f32 v[196:197], v[22:23], v[22:23]
	v_pk_fma_f32 v[196:197], v[24:25], v[24:25], v[196:197]
	v_pk_fma_f32 v[196:197], v[18:19], v[18:19], v[196:197]
	v_pk_fma_f32 v[196:197], v[20:21], v[20:21], v[196:197]
	v_pk_fma_f32 v[196:197], v[6:7], v[6:7], v[196:197]
	v_pk_fma_f32 v[196:197], v[8:9], v[8:9], v[196:197]
	v_pk_fma_f32 v[196:197], v[2:3], v[2:3], v[196:197]
	v_pk_fma_f32 v[196:197], v[4:5], v[4:5], v[196:197]
	s_nop 0
	v_add_f32_e32 v189, v196, v197
	v_mov_b32_e32 v130, v18
	v_mov_b32_e32 v131, v19
	v_mov_b32_e32 v132, v20
	v_mov_b32_e32 v133, v21
	v_mov_b32_e32 v134, v14
	v_mov_b32_e32 v135, v15
	v_mov_b32_e32 v136, v16
	v_mov_b32_e32 v137, v17
	v_mov_b32_e32 v138, v10
	v_mov_b32_e32 v139, v11
	v_mov_b32_e32 v140, v12
	v_mov_b32_e32 v141, v13
	v_mov_b32_e32 v142, v6
	v_mov_b32_e32 v143, v7
	v_mov_b32_e32 v144, v8
	v_mov_b32_e32 v145, v9
	v_mov_b32_e32 v146, v2
	v_mov_b32_e32 v147, v3
	v_mov_b32_e32 v148, v4
	v_mov_b32_e32 v149, v5
	s_and_b64 vcc, exec, s[36:37]
	s_mov_b64 s[42:43], s[38:39]
	s_mov_b64 s[44:45], s[34:35]
	s_branch .Lfz_p1_ret
